# grid barrier: last-arriving XCD leader bumps all local release generations directly (one relay hop less)
# speedup vs baseline: 1.0286x; 1.0077x over previous
; __device__ __forceinline__ unsigned xb_ld(unsigned* p)              { return __hip_atomic_load(p, __ATOMIC_RELAXED, __HIP_MEMORY_SCOPE_AGENT); }
; __device__ __forceinline__ unsigned xb_add(unsigned* p, unsigned v) { return __hip_atomic_fetch_add(p, v, __ATOMIC_RELAXED, __HIP_MEMORY_SCOPE_AGENT); }
; #define XB_SPIN(cond, bar) do { unsigned _sp = 0; while (cond) { __builtin_amdgcn_s_sleep(1); \
;     if ((++_sp & 255u) == 0u) { if (xb_ld(&(bar)[XB_TMO])) break; if (_sp > XB_SPIN_CAP) { atomicAdd(&(bar)[XB_TMO], 1u); break; } } } } while (0)
; __device__ __forceinline__ void xcd_barrier(const XcdBarrier& b) {
;     ...
;         if (old + 1u == (gen + 1u) * nloc) {
;             __builtin_amdgcn_fence(__ATOMIC_RELEASE, "agent");
;             asm volatile("s_waitcnt vmcnt(0)" ::: "memory");
;             const unsigned og = xb_add(&bar[XB_TOP], 1u);
;             const unsigned tg = og / nx;
;             if (og + 1u == (tg + 1u) * nx) xb_add(&bar[XB_TOPGEN], 1u);
;             else XB_SPIN(xb_ld(&bar[XB_TOPGEN]) == tg, bar);
;             __builtin_amdgcn_fence(__ATOMIC_ACQUIRE, "agent");
;             xb_add(&bar[XB_XGEN(b.x)], 1u);
.LBB0_1177:
	s_or_b64 exec, exec, s[18:19]
	s_and_saveexec_b64 s[2:3], s[38:39]
	s_cbranch_execz .LBB0_1179
	v_readlane_b32 s100, v254, 46
	v_readlane_b32 s101, v254, 47
	v_mov_b32_e32 v3, 1
	s_sub_u32 s100, s100, 0x1100
	s_subb_u32 s101, s101, 0
	s_nop 1

; __device__ __forceinline__ unsigned xb_ld(unsigned* p)              { return __hip_atomic_load(p, __ATOMIC_RELAXED, __HIP_MEMORY_SCOPE_AGENT); }
; __device__ __forceinline__ unsigned xb_add(unsigned* p, unsigned v) { return __hip_atomic_fetch_add(p, v, __ATOMIC_RELAXED, __HIP_MEMORY_SCOPE_AGENT); }
; #define XB_SPIN(cond, bar) do { unsigned _sp = 0; while (cond) { __builtin_amdgcn_s_sleep(1); \
;     if ((++_sp & 255u) == 0u) { if (xb_ld(&(bar)[XB_TMO])) break; if (_sp > XB_SPIN_CAP) { atomicAdd(&(bar)[XB_TMO], 1u); break; } } } } while (0)
; __device__ __forceinline__ void xcd_barrier(const XcdBarrier& b) {
;     ...
;             const unsigned og = xb_add(&bar[XB_TOP], 1u);
;             const unsigned tg = og / nx;
;             if (og + 1u == (tg + 1u) * nx) xb_add(&bar[XB_TOPGEN], 1u);
;             else XB_SPIN(xb_ld(&bar[XB_TOPGEN]) == tg, bar);
;             __builtin_amdgcn_fence(__ATOMIC_ACQUIRE, "agent");
;             xb_add(&bar[XB_XGEN(b.x)], 1u);
	global_atomic_add v181, v3, s[100:101]
	global_atomic_add v181, v3, s[100:101] offset:256
	global_atomic_add v181, v3, s[100:101] offset:512
	global_atomic_add v181, v3, s[100:101] offset:768
	global_atomic_add v181, v3, s[100:101] offset:1024
	global_atomic_add v181, v3, s[100:101] offset:1280
	global_atomic_add v181, v3, s[100:101] offset:1536
	global_atomic_add v181, v3, s[100:101] offset:1792
	global_atomic_add v[0:1], v203, off
	global_atomic_add v181, v3, s[100:101] offset:2048
	global_atomic_add v181, v3, s[100:101] offset:2304
	global_atomic_add v181, v3, s[100:101] offset:2560
	global_atomic_add v181, v3, s[100:101] offset:2816
	global_atomic_add v181, v3, s[100:101] offset:3072
	global_atomic_add v181, v3, s[100:101] offset:3328
	global_atomic_add v181, v3, s[100:101] offset:3584
	global_atomic_add v181, v3, s[100:101] offset:3840
.LBB0_1179:
	s_or_b64 exec, exec, s[2:3]
	s_mov_b64 s[2:3], exec
	v_mbcnt_lo_u32_b32 v0, s2, 0
	v_mbcnt_hi_u32_b32 v0, s3, v0
	v_cmp_eq_u32_e32 vcc, 0, v0
	s_waitcnt vmcnt(0)
	buffer_inv sc1
	s_and_saveexec_b64 s[18:19], vcc
	s_cbranch_execz .LBB0_16
	s_branch .LBB0_16
